# v042
# speedup vs baseline: 1.0024x; 1.0024x over previous
.LBB0_25:
	s_and_b32 s0, 0xffff, s26
	v_cvt_f32_i32_e32 v86, s0
	s_sext_i32_i16 s0, s4
	v_cvt_f32_i32_e32 v87, s0
	s_ashr_i32 s0, s0, 30
	v_rcp_iflag_f32_e32 v88, v86
	s_or_b32 s14, s0, 1
	v_mul_f32_e32 v88, v87, v88
	v_trunc_f32_e32 v88, v88
	v_fma_f32 v87, -v88, v86, v87
	v_cvt_i32_f32_e32 v88, v88
	v_cmp_ge_f32_e64 s[0:1], |v87|, v86
	s_and_b64 s[0:1], s[0:1], exec
	s_cselect_b32 s0, s14, 0
	v_readfirstlane_b32 s27, v88
	s_add_i32 s27, s27, s0
	s_sext_i32_i16 s0, s27
	s_lshl_b32 s14, s0, 6
	s_cmp_lg_u64 s[16:17], 0
	s_cselect_b64 s[18:19], -1, 0
	s_cmp_eq_u64 s[16:17], 0
	s_cbranch_scc1 .LBB0_84
	v_add_u32_e32 v86, s14, v36
	v_ashrrev_i32_e32 v87, 31, v86
	v_lshl_add_u64 v[86:87], v[86:87], 2, s[16:17]
	global_load_dword v130, v[86:87], off
	global_load_dword v131, v[86:87], off offset:8
	global_load_dword v132, v[86:87], off offset:16
	global_load_dword v133, v[86:87], off offset:24
	global_load_dword v134, v[86:87], off offset:32
	global_load_dword v135, v[86:87], off offset:40
	global_load_dword v136, v[86:87], off offset:48
	global_load_dword v137, v[86:87], off offset:56
	global_load_dword v138, v[86:87], off offset:64
	global_load_dword v139, v[86:87], off offset:72
	global_load_dword v140, v[86:87], off offset:80
	global_load_dword v141, v[86:87], off offset:88
	global_load_dword v142, v[86:87], off offset:96
	global_load_dword v143, v[86:87], off offset:104
	global_load_dword v144, v[86:87], off offset:112
	global_load_dword v145, v[86:87], off offset:120
	global_load_dword v146, v[86:87], off offset:128
	global_load_dword v147, v[86:87], off offset:136
	global_load_dword v148, v[86:87], off offset:144
	global_load_dword v149, v[86:87], off offset:152
	global_load_dword v150, v[86:87], off offset:160
	global_load_dword v151, v[86:87], off offset:168
	global_load_dword v152, v[86:87], off offset:176
	global_load_dword v153, v[86:87], off offset:184
	global_load_dword v154, v[86:87], off offset:192
	global_load_dword v155, v[86:87], off offset:200
	global_load_dword v156, v[86:87], off offset:208
	global_load_dword v157, v[86:87], off offset:216
	global_load_dword v158, v[86:87], off offset:224
	global_load_dword v159, v[86:87], off offset:232
	global_load_dword v160, v[86:87], off offset:240
	global_load_dword v161, v[86:87], off offset:248
	s_waitcnt vmcnt(30)
	v_mov_b32_e32 v89, v130
	v_mov_b32_e32 v88, v131
	v_mul_f32_e32 v87, v2, v89
	s_cbranch_execnz .LBB0_28

.LBB0_28:
	v_cndmask_b32_e64 v89, 0, 1, s[18:19]
	v_add_u32_e32 v86, v33, v35
	s_waitcnt vmcnt(30)
	v_mul_f32_e32 v88, v1, v88
	v_cmp_ne_u32_e64 s[0:1], 1, v89
	s_andn2_b64 vcc, exec, s[18:19]
	ds_write2_b32 v86, v87, v88 offset1:66
	s_cbranch_vccnz .LBB0_85
	s_ashr_i32 s15, s14, 31
	v_lshl_add_u64 v[88:89], s[14:15], 0, v[36:37]
	v_lshl_add_u64 v[88:89], v[88:89], 2, s[16:17]
	s_nop 0
	s_waitcnt vmcnt(28)
	v_mov_b32_e32 v87, v132
	v_mov_b32_e32 v88, v133
	v_mul_f32_e32 v87, v4, v87
	s_cbranch_execnz .LBB0_31

.LBB0_31:
	s_waitcnt vmcnt(28)
	v_mul_f32_e32 v88, v3, v88
	s_and_b64 vcc, exec, s[0:1]
	ds_write2_b32 v46, v87, v88 offset1:66
	s_cbranch_vccnz .LBB0_86
	s_ashr_i32 s15, s14, 31
	v_lshl_add_u64 v[88:89], s[14:15], 0, v[36:37]
	v_lshl_add_u64 v[88:89], v[88:89], 2, s[16:17]
	s_nop 0
	s_waitcnt vmcnt(26)
	v_mov_b32_e32 v87, v134
	v_mov_b32_e32 v88, v135
	v_mul_f32_e32 v87, v6, v87
	s_cbranch_execnz .LBB0_34

.LBB0_34:
	s_waitcnt vmcnt(26)
	v_mul_f32_e32 v88, v5, v88
	s_and_b64 vcc, exec, s[0:1]
	ds_write2_b32 v47, v87, v88 offset1:66
	s_cbranch_vccnz .LBB0_87
	s_ashr_i32 s15, s14, 31
	v_lshl_add_u64 v[88:89], s[14:15], 0, v[36:37]
	v_lshl_add_u64 v[88:89], v[88:89], 2, s[16:17]
	s_nop 0
	s_waitcnt vmcnt(24)
	v_mov_b32_e32 v87, v136
	v_mov_b32_e32 v88, v137
	v_mul_f32_e32 v87, v8, v87
	s_cbranch_execnz .LBB0_37

.LBB0_37:
	s_waitcnt vmcnt(24)
	v_mul_f32_e32 v88, v7, v88
	s_and_b64 vcc, exec, s[0:1]
	ds_write2_b32 v48, v87, v88 offset1:66
	s_cbranch_vccnz .LBB0_88
	s_ashr_i32 s15, s14, 31
	v_lshl_add_u64 v[88:89], s[14:15], 0, v[36:37]
	v_lshl_add_u64 v[88:89], v[88:89], 2, s[16:17]
	s_nop 0
	s_waitcnt vmcnt(22)
	v_mov_b32_e32 v87, v138
	v_mov_b32_e32 v88, v139
	v_mul_f32_e32 v87, v10, v87
	s_cbranch_execnz .LBB0_40

.LBB0_40:
	s_waitcnt vmcnt(22)
	v_mul_f32_e32 v88, v9, v88
	s_and_b64 vcc, exec, s[0:1]
	ds_write2_b32 v49, v87, v88 offset1:66
	s_cbranch_vccnz .LBB0_89
	s_ashr_i32 s15, s14, 31
	v_lshl_add_u64 v[88:89], s[14:15], 0, v[36:37]
	v_lshl_add_u64 v[88:89], v[88:89], 2, s[16:17]
	s_nop 0
	s_waitcnt vmcnt(20)
	v_mov_b32_e32 v87, v140
	v_mov_b32_e32 v88, v141
	v_mul_f32_e32 v87, v12, v87
	s_cbranch_execnz .LBB0_43

.LBB0_43:
	s_waitcnt vmcnt(20)
	v_mul_f32_e32 v88, v11, v88
	s_and_b64 vcc, exec, s[0:1]
	ds_write2_b32 v50, v87, v88 offset1:66
	s_cbranch_vccnz .LBB0_90
	s_ashr_i32 s15, s14, 31
	v_lshl_add_u64 v[88:89], s[14:15], 0, v[36:37]
	v_lshl_add_u64 v[88:89], v[88:89], 2, s[16:17]
	s_nop 0
	s_waitcnt vmcnt(18)
	v_mov_b32_e32 v87, v142
	v_mov_b32_e32 v88, v143
	v_mul_f32_e32 v87, v14, v87
	s_cbranch_execnz .LBB0_46

.LBB0_46:
	s_waitcnt vmcnt(18)
	v_mul_f32_e32 v88, v13, v88
	s_and_b64 vcc, exec, s[0:1]
	ds_write2_b32 v51, v87, v88 offset1:66
	s_cbranch_vccnz .LBB0_91
	s_ashr_i32 s15, s14, 31
	v_lshl_add_u64 v[88:89], s[14:15], 0, v[36:37]
	v_lshl_add_u64 v[88:89], v[88:89], 2, s[16:17]
	s_nop 0
	s_waitcnt vmcnt(16)
	v_mov_b32_e32 v87, v144
	v_mov_b32_e32 v88, v145
	v_mul_f32_e32 v87, v16, v87
	s_cbranch_execnz .LBB0_49

.LBB0_49:
	s_waitcnt vmcnt(16)
	v_mul_f32_e32 v88, v15, v88
	s_and_b64 vcc, exec, s[0:1]
	ds_write2_b32 v52, v87, v88 offset1:66
	s_cbranch_vccnz .LBB0_92
	s_ashr_i32 s15, s14, 31
	v_lshl_add_u64 v[88:89], s[14:15], 0, v[36:37]
	v_lshl_add_u64 v[88:89], v[88:89], 2, s[16:17]
	s_nop 0
	s_waitcnt vmcnt(14)
	v_mov_b32_e32 v87, v146
	v_mov_b32_e32 v88, v147
	v_mul_f32_e32 v87, v18, v87
	s_cbranch_execnz .LBB0_52

.LBB0_52:
	s_waitcnt vmcnt(14)
	v_mul_f32_e32 v88, v17, v88
	s_and_b64 vcc, exec, s[0:1]
	ds_write2_b32 v53, v87, v88 offset1:66
	s_cbranch_vccnz .LBB0_93
	s_ashr_i32 s15, s14, 31
	v_lshl_add_u64 v[88:89], s[14:15], 0, v[36:37]
	v_lshl_add_u64 v[88:89], v[88:89], 2, s[16:17]
	s_nop 0
	s_waitcnt vmcnt(12)
	v_mov_b32_e32 v87, v148
	v_mov_b32_e32 v88, v149
	v_mul_f32_e32 v87, v20, v87
	s_cbranch_execnz .LBB0_55

.LBB0_55:
	s_waitcnt vmcnt(12)
	v_mul_f32_e32 v88, v19, v88
	s_and_b64 vcc, exec, s[0:1]
	ds_write2_b32 v53, v87, v88 offset0:132 offset1:198
	s_cbranch_vccnz .LBB0_94
	s_ashr_i32 s15, s14, 31
	v_lshl_add_u64 v[88:89], s[14:15], 0, v[36:37]
	v_lshl_add_u64 v[88:89], v[88:89], 2, s[16:17]
	s_waitcnt vmcnt(10)
	v_mov_b32_e32 v90, v150
	v_mov_b32_e32 v87, v151
	v_mul_f32_e32 v88, v22, v90
	s_cbranch_execnz .LBB0_58

.LBB0_58:
	s_waitcnt vmcnt(10)
	v_mul_f32_e32 v89, v21, v87
	v_add_u32_e32 v87, 0x400, v53
	s_and_b64 vcc, exec, s[0:1]
	ds_write2_b32 v87, v88, v89 offset0:8 offset1:74
	s_cbranch_vccnz .LBB0_95
	s_ashr_i32 s15, s14, 31
	v_lshl_add_u64 v[88:89], s[14:15], 0, v[36:37]
	v_lshl_add_u64 v[88:89], v[88:89], 2, s[16:17]
	s_nop 0
	s_waitcnt vmcnt(8)
	v_mov_b32_e32 v90, v152
	v_mov_b32_e32 v89, v153
	v_mul_f32_e32 v88, v24, v90
	s_cbranch_execnz .LBB0_61

.LBB0_61:
	s_waitcnt vmcnt(8)
	v_mul_f32_e32 v89, v23, v89
	s_and_b64 vcc, exec, s[0:1]
	ds_write2_b32 v87, v88, v89 offset0:140 offset1:206
	s_cbranch_vccnz .LBB0_96
	s_ashr_i32 s15, s14, 31
	v_lshl_add_u64 v[88:89], s[14:15], 0, v[36:37]
	v_lshl_add_u64 v[88:89], v[88:89], 2, s[16:17]
	s_nop 0
	s_waitcnt vmcnt(6)
	v_mov_b32_e32 v90, v154
	v_mov_b32_e32 v88, v155
	v_mul_f32_e32 v89, v26, v90
	s_cbranch_execnz .LBB0_64

.LBB0_64:
	s_waitcnt vmcnt(6)
	v_mul_f32_e32 v90, v25, v88
	v_add_u32_e32 v88, 0x800, v53
	s_and_b64 vcc, exec, s[0:1]
	ds_write2_b32 v88, v89, v90 offset0:16 offset1:82
	s_cbranch_vccnz .LBB0_97
	s_ashr_i32 s15, s14, 31
	v_lshl_add_u64 v[90:91], s[14:15], 0, v[36:37]
	v_lshl_add_u64 v[90:91], v[90:91], 2, s[16:17]
	s_nop 0
	s_waitcnt vmcnt(4)
	v_mov_b32_e32 v89, v156
	v_mov_b32_e32 v90, v157
	v_mul_f32_e32 v89, v28, v89
	s_cbranch_execnz .LBB0_67

.LBB0_67:
	s_waitcnt vmcnt(4)
	v_mul_f32_e32 v90, v27, v90
	s_and_b64 vcc, exec, s[0:1]
	ds_write2_b32 v88, v89, v90 offset0:148 offset1:214
	s_cbranch_vccnz .LBB0_98
	s_ashr_i32 s15, s14, 31
	v_lshl_add_u64 v[90:91], s[14:15], 0, v[36:37]
	v_lshl_add_u64 v[90:91], v[90:91], 2, s[16:17]
	s_waitcnt vmcnt(2)
	v_mov_b32_e32 v92, v158
	v_mov_b32_e32 v89, v159
	v_mul_f32_e32 v90, v30, v92
	s_cbranch_execnz .LBB0_70

.LBB0_70:
	s_waitcnt vmcnt(2)
	v_mul_f32_e32 v91, v29, v89
	v_add_u32_e32 v89, 0xc00, v53
	s_and_b64 vcc, exec, s[0:1]
	ds_write2_b32 v89, v90, v91 offset0:24 offset1:90
	s_cbranch_vccnz .LBB0_99
	s_ashr_i32 s15, s14, 31
	v_lshl_add_u64 v[90:91], s[14:15], 0, v[36:37]
	v_lshl_add_u64 v[90:91], v[90:91], 2, s[16:17]
	s_nop 0
	s_waitcnt vmcnt(0)
	v_mov_b32_e32 v92, v160
	v_mov_b32_e32 v91, v161
	v_mul_f32_e32 v90, v32, v92
	s_cbranch_execnz .LBB0_73

.LBB0_101:
	s_and_b32 s0, 0xffff, s18
	v_cvt_f32_i32_e32 v90, s0
	s_sext_i32_i16 s0, s4
	v_cvt_f32_i32_e32 v91, s0
	s_ashr_i32 s0, s0, 30
	v_rcp_iflag_f32_e32 v92, v90
	s_or_b32 s12, s0, 1
	v_mul_f32_e32 v92, v91, v92
	v_trunc_f32_e32 v92, v92
	v_fma_f32 v91, -v92, v90, v91
	v_cvt_i32_f32_e32 v92, v92
	v_cmp_ge_f32_e64 s[0:1], |v91|, v90
	s_and_b64 s[0:1], s[0:1], exec
	s_cselect_b32 s0, s12, 0
	v_readfirstlane_b32 s19, v92
	s_add_i32 s19, s19, s0
	s_sext_i32_i16 s0, s19
	s_lshl_b32 s12, s0, 6
	s_cmp_lg_u64 s[14:15], 0
	s_cselect_b64 s[16:17], -1, 0
	s_cmp_eq_u64 s[14:15], 0
	s_cbranch_scc1 .LBB0_124
	v_add_u32_e32 v90, s12, v36
	v_ashrrev_i32_e32 v91, 31, v90
	v_lshl_add_u64 v[90:91], v[90:91], 2, s[14:15]
	global_load_dword v130, v[90:91], off
	global_load_dword v131, v[90:91], off offset:8
	global_load_dword v132, v[90:91], off offset:16
	global_load_dword v133, v[90:91], off offset:24
	global_load_dword v134, v[90:91], off offset:32
	global_load_dword v135, v[90:91], off offset:40
	global_load_dword v136, v[90:91], off offset:48
	global_load_dword v137, v[90:91], off offset:56
	global_load_dword v138, v[90:91], off offset:64
	global_load_dword v139, v[90:91], off offset:72
	global_load_dword v140, v[90:91], off offset:80
	global_load_dword v141, v[90:91], off offset:88
	global_load_dword v142, v[90:91], off offset:96
	global_load_dword v143, v[90:91], off offset:104
	global_load_dword v144, v[90:91], off offset:112
	global_load_dword v145, v[90:91], off offset:120
	global_load_dword v146, v[90:91], off offset:128
	global_load_dword v147, v[90:91], off offset:136
	global_load_dword v148, v[90:91], off offset:144
	global_load_dword v149, v[90:91], off offset:152
	global_load_dword v150, v[90:91], off offset:160
	global_load_dword v151, v[90:91], off offset:168
	global_load_dword v152, v[90:91], off offset:176
	global_load_dword v153, v[90:91], off offset:184
	global_load_dword v154, v[90:91], off offset:192
	global_load_dword v155, v[90:91], off offset:200
	global_load_dword v156, v[90:91], off offset:208
	global_load_dword v157, v[90:91], off offset:216
	global_load_dword v158, v[90:91], off offset:224
	global_load_dword v159, v[90:91], off offset:232
	global_load_dword v160, v[90:91], off offset:240
	global_load_dword v161, v[90:91], off offset:248
	s_nop 0
	s_waitcnt vmcnt(28)
	v_mov_b32_e32 v92, v130
	v_mov_b32_e32 v93, v131
	v_mov_b32_e32 v94, v132
	v_mov_b32_e32 v91, v133
	v_mul_f32_e32 v92, v54, v92
	s_waitcnt vmcnt(28)
	v_mul_f32_e32 v93, v55, v93
	s_waitcnt vmcnt(28)
	v_mul_f32_e32 v90, v56, v94
	ds_write2_b32 v86, v92, v93 offset1:66
	s_cbranch_execnz .LBB0_104

.LBB0_104:
	s_waitcnt vmcnt(28)
	v_mul_f32_e32 v86, v58, v91
	v_cndmask_b32_e64 v91, 0, 1, s[16:17]
	v_cmp_ne_u32_e64 s[0:1], 1, v91
	s_andn2_b64 vcc, exec, s[16:17]
	ds_write2_b32 v46, v90, v86 offset1:66
	s_cbranch_vccnz .LBB0_125
	s_ashr_i32 s13, s12, 31
	v_lshl_add_u64 v[90:91], s[12:13], 0, v[36:37]
	v_lshl_add_u64 v[90:91], v[90:91], 2, s[14:15]
	s_waitcnt vmcnt(24)
	v_mov_b32_e32 v92, v134
	v_mov_b32_e32 v93, v135
	v_mov_b32_e32 v94, v136
	v_mov_b32_e32 v86, v137
	v_mul_f32_e32 v91, v61, v92
	s_waitcnt vmcnt(24)
	v_mul_f32_e32 v92, v64, v93
	s_waitcnt vmcnt(24)
	v_mul_f32_e32 v90, v67, v94
	ds_write2_b32 v47, v91, v92 offset1:66
	s_cbranch_execnz .LBB0_107

.LBB0_107:
	s_waitcnt vmcnt(24)
	v_mul_f32_e32 v86, v57, v86
	s_and_b64 vcc, exec, s[0:1]
	ds_write2_b32 v48, v90, v86 offset1:66
	s_cbranch_vccnz .LBB0_126
	s_ashr_i32 s13, s12, 31
	v_lshl_add_u64 v[90:91], s[12:13], 0, v[36:37]
	v_lshl_add_u64 v[90:91], v[90:91], 2, s[14:15]
	s_waitcnt vmcnt(20)
	v_mov_b32_e32 v92, v138
	v_mov_b32_e32 v93, v139
	v_mov_b32_e32 v94, v140
	v_mov_b32_e32 v86, v141
	v_mul_f32_e32 v91, v59, v92
	s_waitcnt vmcnt(20)
	v_mul_f32_e32 v92, v60, v93
	s_waitcnt vmcnt(20)
	v_mul_f32_e32 v90, v62, v94
	ds_write2_b32 v49, v91, v92 offset1:66
	s_cbranch_execnz .LBB0_110

.LBB0_110:
	s_waitcnt vmcnt(20)
	v_mul_f32_e32 v86, v63, v86
	s_and_b64 vcc, exec, s[0:1]
	ds_write2_b32 v50, v90, v86 offset1:66
	s_cbranch_vccnz .LBB0_127
	s_ashr_i32 s13, s12, 31
	v_lshl_add_u64 v[90:91], s[12:13], 0, v[36:37]
	v_lshl_add_u64 v[90:91], v[90:91], 2, s[14:15]
	s_waitcnt vmcnt(16)
	v_mov_b32_e32 v92, v142
	v_mov_b32_e32 v93, v143
	v_mov_b32_e32 v94, v144
	v_mov_b32_e32 v86, v145
	v_mul_f32_e32 v91, v65, v92
	s_waitcnt vmcnt(16)
	v_mul_f32_e32 v92, v66, v93
	s_waitcnt vmcnt(16)
	v_mul_f32_e32 v90, v68, v94
	ds_write2_b32 v51, v91, v92 offset1:66
	s_cbranch_execnz .LBB0_113

.LBB0_113:
	s_waitcnt vmcnt(16)
	v_mul_f32_e32 v86, v69, v86
	s_and_b64 vcc, exec, s[0:1]
	ds_write2_b32 v52, v90, v86 offset1:66
	s_cbranch_vccnz .LBB0_128
	s_ashr_i32 s13, s12, 31
	v_lshl_add_u64 v[90:91], s[12:13], 0, v[36:37]
	v_lshl_add_u64 v[90:91], v[90:91], 2, s[14:15]
	s_waitcnt vmcnt(12)
	v_mov_b32_e32 v92, v146
	v_mov_b32_e32 v93, v147
	v_mov_b32_e32 v94, v148
	v_mov_b32_e32 v86, v149
	v_mul_f32_e32 v91, v70, v92
	s_waitcnt vmcnt(12)
	v_mul_f32_e32 v92, v71, v93
	s_waitcnt vmcnt(12)
	v_mul_f32_e32 v90, v72, v94
	ds_write2_b32 v53, v91, v92 offset1:66
	s_cbranch_execnz .LBB0_116

.LBB0_116:
	s_waitcnt vmcnt(12)
	v_mul_f32_e32 v86, v73, v86
	s_and_b64 vcc, exec, s[0:1]
	ds_write2_b32 v53, v90, v86 offset0:132 offset1:198
	s_cbranch_vccnz .LBB0_129
	s_ashr_i32 s13, s12, 31
	v_lshl_add_u64 v[90:91], s[12:13], 0, v[36:37]
	v_lshl_add_u64 v[90:91], v[90:91], 2, s[14:15]
	s_waitcnt vmcnt(8)
	v_mov_b32_e32 v92, v150
	v_mov_b32_e32 v93, v151
	v_mov_b32_e32 v94, v152
	v_mov_b32_e32 v86, v153
	v_mul_f32_e32 v91, v74, v92
	s_waitcnt vmcnt(8)
	v_mul_f32_e32 v92, v75, v93
	s_waitcnt vmcnt(8)
	v_mul_f32_e32 v90, v76, v94
	ds_write2_b32 v87, v91, v92 offset0:8 offset1:74
	s_cbranch_execnz .LBB0_119

.LBB0_119:
	s_waitcnt vmcnt(8)
	v_mul_f32_e32 v86, v77, v86
	s_and_b64 vcc, exec, s[0:1]
	ds_write2_b32 v87, v90, v86 offset0:140 offset1:206
	s_cbranch_vccnz .LBB0_130
	s_ashr_i32 s13, s12, 31
	v_lshl_add_u64 v[86:87], s[12:13], 0, v[36:37]
	v_lshl_add_u64 v[86:87], v[86:87], 2, s[14:15]
	s_nop 0
	s_waitcnt vmcnt(4)
	v_mov_b32_e32 v90, v154
	v_mov_b32_e32 v91, v155
	v_mov_b32_e32 v92, v156
	v_mov_b32_e32 v86, v157
	v_mul_f32_e32 v90, v78, v90
	s_waitcnt vmcnt(4)
	v_mul_f32_e32 v91, v79, v91
	s_waitcnt vmcnt(4)
	v_mul_f32_e32 v87, v80, v92
	ds_write2_b32 v88, v90, v91 offset0:16 offset1:82
	s_cbranch_execnz .LBB0_122

.LBB0_122:
	s_waitcnt vmcnt(4)
	v_mul_f32_e32 v86, v81, v86
	s_and_b64 vcc, exec, s[0:1]
	ds_write2_b32 v88, v87, v86 offset0:148 offset1:214
	s_cbranch_vccnz .LBB0_131
	s_ashr_i32 s13, s12, 31
	v_lshl_add_u64 v[86:87], s[12:13], 0, v[36:37]
	v_lshl_add_u64 v[86:87], v[86:87], 2, s[14:15]
	s_nop 0
	s_waitcnt vmcnt(0)
	v_mov_b32_e32 v88, v158
	v_mov_b32_e32 v90, v159
	v_mov_b32_e32 v91, v160
	v_mov_b32_e32 v86, v161
	v_mul_f32_e32 v88, v82, v88
	s_waitcnt vmcnt(0)
	v_mul_f32_e32 v90, v83, v90
	s_waitcnt vmcnt(0)
	v_mul_f32_e32 v87, v84, v91
	ds_write2_b32 v89, v88, v90 offset0:24 offset1:90
	s_cbranch_execnz .LBB0_12
	s_branch .LBB0_11
